# first K iteration after an epilogue: first two tile waits count the epilogue's >=16 (residual: >=88) younger VMEM ops instead of draining them
# baseline (speedup 1.0000x reference)
; #define PG8_STAGE(bufoff, gbase, voff) do { _Pragma("unroll") for (int _i = 0; _i < 2; ++_i) \
;         __builtin_amdgcn_global_load_lds((const unsigned*)((const char*)(gbase) + (voff)[_i]), (LAS unsigned*)(lds + (bufoff) + ldsw + _i * 8192), 16, 0, 0); } while (0)
; #define PG8_LDA(dst, b, h) do { _Pragma("unroll") for (int m = 0; m < 4; ++m) _Pragma("unroll") for (int k = 0; k < 2; ++k) dst[m][k] = *(const LAS bf16x8*)(lds + PG8_SA(b, h) + aoff + m * 2048 + k * 1024); } while (0)
; #define PG8_LDB(dst, b, h) do { _Pragma("unroll") for (int n = 0; n < 2; ++n) _Pragma("unroll") for (int k = 0; k < 2; ++k) dst[n][k] = *(const LAS bf16x8*)(lds + PG8_SB(b, h) + boff + n * 2048 + k * 1024); } while (0)
; #define PG8_MMA(ai, bj, At, Bt) do { __builtin_amdgcn_s_setprio(1); _Pragma("unroll") for (int m = 0; m < 4; ++m) _Pragma("unroll") for (int n = 0; n < 2; ++n) _Pragma("unroll") for (int k = 0; k < 2; ++k) \
;         acc[ai][bj][m][n] = __builtin_amdgcn_mfma_f32_16x16x32_bf16(Bt[n][k], At[m][k], acc[ai][bj][m][n], 0, 0, 0); __builtin_amdgcn_s_setprio(0); } while (0)
; #define PG8_WAIT_L(n) asm volatile("s_waitcnt lgkmcnt(" #n ")" ::: "memory")
; #define PG8_BAR __builtin_amdgcn_s_barrier()
; #define PG8_SCHED __builtin_amdgcn_sched_barrier(0)
; template <class Epi>
; __device__ __forceinline__ void gemm_phase(LAS unsigned char* lds, const Gemm g, const StaticOrder& S, const Epi& E, const bool perm) {
;     ...
;             PG8_LDB(B0, 0, 0); PG8_SCHED; PG8_LDA(At, 0, 0); PG8_STAGE(PG8_SA(1, 1), a1 + hstep, voffA);
;             PG8_WAIT_L(8); PG8_BAR; PG8_WAIT_L(0); PG8_MMA(0, 0, At, B0); PG8_BAR; PG8_SCHED;
.Lk_first:
	s_add_i32 s61, s60, 2
	s_add_u32 s22, s6, 0x80
	s_addc_u32 s23, s7, 0
	s_add_i32 s40, 0, 0x10000
	v_add_u32_e32 v140, s40, v245
	s_waitcnt lgkmcnt(0)
	ds_read_b128 v[128:131], v140
	ds_read_b128 v[132:135], v140 offset:1024
	ds_read_b128 v[136:139], v140 offset:2048
	ds_read_b128 v[140:143], v140 offset:3072
	s_cmp_eq_u32 s27, s60
	s_cselect_b32 s23, s1, s23
	s_cselect_b32 s22, s0, s22
	s_cselect_b32 s47, s13, s78
	s_cselect_b32 s46, s12, s55
	v_lshl_add_u64 v[176:177], s[6:7], 0, v[214:215]
	s_add_i32 m0, s36, 0xc000
	ds_read_b128 v[144:147], v248
	ds_read_b128 v[148:151], v248 offset:1024
	ds_read_b128 v[152:155], v248 offset:2048
	ds_read_b128 v[156:159], v248 offset:3072
	ds_read_b128 v[160:163], v248 offset:4096
	ds_read_b128 v[164:167], v248 offset:5120
	ds_read_b128 v[168:171], v248 offset:6144
	ds_read_b128 v[172:175], v248 offset:7168
	global_load_lds_dwordx4 v[176:177], off
	v_lshl_add_u64 v[176:177], s[6:7], 0, v[216:217]
	s_add_i32 m0, s36, 0xe000
	s_nop 0
	global_load_lds_dwordx4 v[176:177], off
	s_add_i32 s60, 0, 0x14000
	s_add_i32 s40, s40, s31
	v_add_u32_e32 v184, s60, v245
	ds_read_b128 v[176:179], v184
	ds_read_b128 v[180:183], v184 offset:1024
	ds_read_b128 v[222:225], v184 offset:2048
	ds_read_b128 v[226:229], v184 offset:3072
	s_cmp_eq_u32 s24, 0
	s_cbranch_scc1 .Lkf_strict1
	s_cmp_eq_u32 s5, 1
	s_cbranch_scc1 .Lkf_res1
	s_waitcnt vmcnt(24)
	s_branch .Lkf_j1
.Lkf_res1:
	s_waitcnt vmcnt(63)
	s_branch .Lkf_j1

; #define PG8_STAGE(bufoff, gbase, voff) do { _Pragma("unroll") for (int _i = 0; _i < 2; ++_i) \
;         __builtin_amdgcn_global_load_lds((const unsigned*)((const char*)(gbase) + (voff)[_i]), (LAS unsigned*)(lds + (bufoff) + ldsw + _i * 8192), 16, 0, 0); } while (0)
; #define PG8_LDA(dst, b, h) do { _Pragma("unroll") for (int m = 0; m < 4; ++m) _Pragma("unroll") for (int k = 0; k < 2; ++k) dst[m][k] = *(const LAS bf16x8*)(lds + PG8_SA(b, h) + aoff + m * 2048 + k * 1024); } while (0)
; #define PG8_LDB(dst, b, h) do { _Pragma("unroll") for (int n = 0; n < 2; ++n) _Pragma("unroll") for (int k = 0; k < 2; ++k) dst[n][k] = *(const LAS bf16x8*)(lds + PG8_SB(b, h) + boff + n * 2048 + k * 1024); } while (0)
; #define PG8_MMA(ai, bj, At, Bt) do { __builtin_amdgcn_s_setprio(1); _Pragma("unroll") for (int m = 0; m < 4; ++m) _Pragma("unroll") for (int n = 0; n < 2; ++n) _Pragma("unroll") for (int k = 0; k < 2; ++k) \
;         acc[ai][bj][m][n] = __builtin_amdgcn_mfma_f32_16x16x32_bf16(Bt[n][k], At[m][k], acc[ai][bj][m][n], 0, 0, 0); __builtin_amdgcn_s_setprio(0); } while (0)
; #define PG8_WAIT_L(n) asm volatile("s_waitcnt lgkmcnt(" #n ")" ::: "memory")
; #define PG8_BAR __builtin_amdgcn_s_barrier()
; #define PG8_SCHED __builtin_amdgcn_sched_barrier(0)
; template <class Epi>
; __device__ __forceinline__ void gemm_phase(LAS unsigned char* lds, const Gemm g, const StaticOrder& S, const Epi& E, const bool perm) {
;     ...
;             PG8_LDB(B0, 0, 0); PG8_SCHED; PG8_LDA(At, 0, 0); PG8_STAGE(PG8_SA(1, 1), a1 + hstep, voffA);
;             PG8_WAIT_L(8); PG8_BAR; PG8_WAIT_L(0); PG8_MMA(0, 0, At, B0); PG8_BAR; PG8_SCHED;
;             PG8_LDB(B1, 0, 1); PG8_STAGE(PG8_SB(0, 0), b2, voffB);
;             PG8_BAR; PG8_WAIT_L(0); PG8_MMA(0, 1, At, B1); PG8_BAR;
;             PG8_LDA(At, 0, 1); PG8_STAGE(PG8_SA(0, 0), a2, voffA);
.Lkf_j1:
	s_waitcnt lgkmcnt(0)
	s_barrier
	s_setprio 1
	v_mfma_f32_16x16x32_bf16 v[124:127], v[128:131], v[144:147], 0
	v_mfma_f32_16x16x32_bf16 v[120:123], v[136:139], v[144:147], 0
	v_mfma_f32_16x16x32_bf16 v[108:111], v[128:131], v[152:155], 0
	v_mfma_f32_16x16x32_bf16 v[104:107], v[136:139], v[152:155], 0
	v_mfma_f32_16x16x32_bf16 v[92:95], v[128:131], v[160:163], 0
	v_mfma_f32_16x16x32_bf16 v[88:91], v[136:139], v[160:163], 0
	v_mfma_f32_16x16x32_bf16 v[76:79], v[128:131], v[168:171], 0
	v_mfma_f32_16x16x32_bf16 v[72:75], v[136:139], v[168:171], 0
	v_mfma_f32_16x16x32_bf16 v[124:127], v[132:135], v[148:151], v[124:127]
	v_mfma_f32_16x16x32_bf16 v[120:123], v[140:143], v[148:151], v[120:123]
	v_mfma_f32_16x16x32_bf16 v[108:111], v[132:135], v[156:159], v[108:111]
	v_mfma_f32_16x16x32_bf16 v[104:107], v[140:143], v[156:159], v[104:107]
	v_mfma_f32_16x16x32_bf16 v[92:95], v[132:135], v[164:167], v[92:95]
	v_mfma_f32_16x16x32_bf16 v[88:91], v[140:143], v[164:167], v[88:91]
	v_mfma_f32_16x16x32_bf16 v[76:79], v[132:135], v[172:175], v[76:79]
	v_mfma_f32_16x16x32_bf16 v[72:75], v[140:143], v[172:175], v[72:75]
	v_mfma_f32_16x16x32_bf16 v[116:119], v[176:179], v[144:147], 0
	v_mfma_f32_16x16x32_bf16 v[112:115], v[222:225], v[144:147], 0
	v_mfma_f32_16x16x32_bf16 v[100:103], v[176:179], v[152:155], 0
	v_mfma_f32_16x16x32_bf16 v[96:99], v[222:225], v[152:155], 0
	v_mfma_f32_16x16x32_bf16 v[84:87], v[176:179], v[160:163], 0
	v_mfma_f32_16x16x32_bf16 v[80:83], v[222:225], v[160:163], 0
	v_mfma_f32_16x16x32_bf16 v[68:71], v[176:179], v[168:171], 0
	v_mfma_f32_16x16x32_bf16 v[64:67], v[222:225], v[168:171], 0
	v_mfma_f32_16x16x32_bf16 v[116:119], v[180:183], v[148:151], v[116:119]
	v_mfma_f32_16x16x32_bf16 v[112:115], v[226:229], v[148:151], v[112:115]
	v_mfma_f32_16x16x32_bf16 v[100:103], v[180:183], v[156:159], v[100:103]
	v_mfma_f32_16x16x32_bf16 v[96:99], v[226:229], v[156:159], v[96:99]
	v_mfma_f32_16x16x32_bf16 v[84:87], v[180:183], v[164:167], v[84:87]
	v_mfma_f32_16x16x32_bf16 v[80:83], v[226:229], v[164:167], v[80:83]
	v_mfma_f32_16x16x32_bf16 v[68:71], v[180:183], v[172:175], v[68:71]
	v_mfma_f32_16x16x32_bf16 v[64:67], v[226:229], v[172:175], v[64:67]
	s_setprio 0
	s_barrier
	ds_read_b128 v[144:147], v248 offset:16384
	ds_read_b128 v[148:151], v248 offset:17408
	ds_read_b128 v[152:155], v248 offset:18432
	ds_read_b128 v[156:159], v248 offset:19456
	ds_read_b128 v[160:163], v248 offset:20480
	ds_read_b128 v[164:167], v248 offset:21504
	ds_read_b128 v[168:171], v248 offset:22528
	ds_read_b128 v[172:175], v248 offset:23552
	v_lshl_add_u64 v[230:231], s[46:47], 0, v[212:213]
	s_mov_b32 m0, s40
	s_nop 0
	global_load_lds_dwordx4 v[230:231], off
	v_lshl_add_u64 v[232:233], s[46:47], 0, v[208:209]
	s_add_i32 m0, s40, 0x2000
	s_nop 0
	global_load_lds_dwordx4 v[232:233], off
	v_lshl_add_u64 v[250:251], s[22:23], 0, v[210:211]
	s_mov_b32 m0, s36
	s_nop 0
	global_load_lds_dwordx4 v[250:251], off
	v_lshl_add_u64 v[252:253], s[22:23], 0, v[206:207]
	s_mov_b32 m0, s37
	s_nop 0
	global_load_lds_dwordx4 v[252:253], off
	s_add_u32 s40, s46, s80
	s_addc_u32 s41, s47, s81
	s_add_i32 s46, s60, s31
	v_lshl_add_u64 v[238:239], s[40:41], 0, v[212:213]
	s_mov_b32 m0, s46
	v_lshl_add_u64 v[240:241], s[40:41], 0, v[208:209]
	global_load_lds_dwordx4 v[238:239], off
	s_add_i32 m0, s46, 0x2000
	s_nop 0
	global_load_lds_dwordx4 v[240:241], off
	s_cmp_eq_u32 s24, 0
	s_cbranch_scc1 .Lkf_strict2
	s_cmp_eq_u32 s5, 1
	s_cbranch_scc1 .Lkf_res2
	s_waitcnt vmcnt(24)
	s_branch .Lkf_j2

; #define PG8_STAGE(bufoff, gbase, voff) do { _Pragma("unroll") for (int _i = 0; _i < 2; ++_i) \
;         __builtin_amdgcn_global_load_lds((const unsigned*)((const char*)(gbase) + (voff)[_i]), (LAS unsigned*)(lds + (bufoff) + ldsw + _i * 8192), 16, 0, 0); } while (0)
; #define PG8_LDA(dst, b, h) do { _Pragma("unroll") for (int m = 0; m < 4; ++m) _Pragma("unroll") for (int k = 0; k < 2; ++k) dst[m][k] = *(const LAS bf16x8*)(lds + PG8_SA(b, h) + aoff + m * 2048 + k * 1024); } while (0)
; #define PG8_LDB(dst, b, h) do { _Pragma("unroll") for (int n = 0; n < 2; ++n) _Pragma("unroll") for (int k = 0; k < 2; ++k) dst[n][k] = *(const LAS bf16x8*)(lds + PG8_SB(b, h) + boff + n * 2048 + k * 1024); } while (0)
; #define PG8_MMA(ai, bj, At, Bt) do { __builtin_amdgcn_s_setprio(1); _Pragma("unroll") for (int m = 0; m < 4; ++m) _Pragma("unroll") for (int n = 0; n < 2; ++n) _Pragma("unroll") for (int k = 0; k < 2; ++k) \
;         acc[ai][bj][m][n] = __builtin_amdgcn_mfma_f32_16x16x32_bf16(Bt[n][k], At[m][k], acc[ai][bj][m][n], 0, 0, 0); __builtin_amdgcn_s_setprio(0); } while (0)
; #define PG8_WAIT_V(n) asm volatile("s_waitcnt vmcnt(" #n ")" ::: "memory")
; #define PG8_WAIT_L(n) asm volatile("s_waitcnt lgkmcnt(" #n ")" ::: "memory")
; #define PG8_BAR __builtin_amdgcn_s_barrier()
; #define PG8_SCHED __builtin_amdgcn_sched_barrier(0)
; template <class Epi>
; __device__ __forceinline__ void gemm_phase(LAS unsigned char* lds, const Gemm g, const StaticOrder& S, const Epi& E, const bool perm) {
;     ...
;             PG8_BAR; PG8_WAIT_L(0); PG8_MMA(1, 0, At, B0); PG8_BAR; PG8_SCHED;
;             PG8_STAGE(PG8_SB(0, 1), b2 + hstep, voffB);
;             PG8_WAIT_V(6); PG8_BAR; PG8_MMA(1, 1, At, B1); PG8_BAR;
;             PG8_LDB(B0, 1, 0); PG8_SCHED; PG8_LDA(At, 1, 0); PG8_STAGE(PG8_SA(0, 1), a2 + hstep, voffA);
;             PG8_WAIT_L(8); PG8_BAR; PG8_WAIT_L(0); PG8_MMA(0, 0, At, B0); PG8_BAR; PG8_SCHED;
.Lkf_j2:
	s_waitcnt lgkmcnt(0)
	s_barrier
	s_setprio 1
	v_mfma_f32_16x16x32_bf16 v[60:63], v[128:131], v[144:147], 0
	v_mfma_f32_16x16x32_bf16 v[56:59], v[136:139], v[144:147], 0
	v_mfma_f32_16x16x32_bf16 v[44:47], v[128:131], v[152:155], 0
	v_mfma_f32_16x16x32_bf16 v[40:43], v[136:139], v[152:155], 0
	v_mfma_f32_16x16x32_bf16 v[28:31], v[128:131], v[160:163], 0
	v_mfma_f32_16x16x32_bf16 v[24:27], v[136:139], v[160:163], 0
	v_mfma_f32_16x16x32_bf16 v[12:15], v[128:131], v[168:171], 0
	v_mfma_f32_16x16x32_bf16 v[8:11], v[136:139], v[168:171], 0
	v_mfma_f32_16x16x32_bf16 v[60:63], v[132:135], v[148:151], v[60:63]
	v_mfma_f32_16x16x32_bf16 v[56:59], v[140:143], v[148:151], v[56:59]
	v_mfma_f32_16x16x32_bf16 v[44:47], v[132:135], v[156:159], v[44:47]
	v_mfma_f32_16x16x32_bf16 v[40:43], v[140:143], v[156:159], v[40:43]
	v_mfma_f32_16x16x32_bf16 v[28:31], v[132:135], v[164:167], v[28:31]
	v_mfma_f32_16x16x32_bf16 v[24:27], v[140:143], v[164:167], v[24:27]
	v_mfma_f32_16x16x32_bf16 v[12:15], v[132:135], v[172:175], v[12:15]
	v_mfma_f32_16x16x32_bf16 v[8:11], v[140:143], v[172:175], v[8:11]
	v_mfma_f32_16x16x32_bf16 v[52:55], v[176:179], v[144:147], 0
	v_mfma_f32_16x16x32_bf16 v[48:51], v[222:225], v[144:147], 0
	v_mfma_f32_16x16x32_bf16 v[36:39], v[176:179], v[152:155], 0
	v_mfma_f32_16x16x32_bf16 v[32:35], v[222:225], v[152:155], 0
	v_mfma_f32_16x16x32_bf16 v[20:23], v[176:179], v[160:163], 0
	v_mfma_f32_16x16x32_bf16 v[16:19], v[222:225], v[160:163], 0
	v_mfma_f32_16x16x32_bf16 v[4:7], v[176:179], v[168:171], 0
	v_mfma_f32_16x16x32_bf16 v[0:3], v[222:225], v[168:171], 0
	v_mfma_f32_16x16x32_bf16 v[52:55], v[180:183], v[148:151], v[52:55]
	v_mfma_f32_16x16x32_bf16 v[48:51], v[226:229], v[148:151], v[48:51]
	v_mfma_f32_16x16x32_bf16 v[36:39], v[180:183], v[156:159], v[36:39]
	v_mfma_f32_16x16x32_bf16 v[32:35], v[226:229], v[156:159], v[32:35]
	v_mfma_f32_16x16x32_bf16 v[20:23], v[180:183], v[164:167], v[20:23]
	v_mfma_f32_16x16x32_bf16 v[16:19], v[226:229], v[164:167], v[16:19]
	v_mfma_f32_16x16x32_bf16 v[4:7], v[180:183], v[172:175], v[4:7]
	v_mfma_f32_16x16x32_bf16 v[0:3], v[226:229], v[172:175], v[0:3]
	s_setprio 0
	s_add_i32 s40, 0, 0x18000
	v_add_u32_e32 v140, s40, v245
	s_barrier
	ds_read_b128 v[128:131], v140
	ds_read_b128 v[132:135], v140 offset:1024
	ds_read_b128 v[136:139], v140 offset:2048
	ds_read_b128 v[140:143], v140 offset:3072
	s_add_u32 s22, s22, s80
	s_addc_u32 s23, s23, s81
	s_mov_b32 m0, s34
	v_lshl_add_u64 v[176:177], s[22:23], 0, v[210:211]
	ds_read_b128 v[144:147], v248 offset:32768
	ds_read_b128 v[148:151], v248 offset:33792
	ds_read_b128 v[152:155], v248 offset:34816
	ds_read_b128 v[156:159], v248 offset:35840
	ds_read_b128 v[160:163], v248 offset:36864
	ds_read_b128 v[164:167], v248 offset:37888
	ds_read_b128 v[168:171], v248 offset:38912
	ds_read_b128 v[172:175], v248 offset:39936
	global_load_lds_dwordx4 v[176:177], off
	v_lshl_add_u64 v[176:177], s[22:23], 0, v[206:207]
	s_mov_b32 m0, s35
	s_nop 0
	global_load_lds_dwordx4 v[176:177], off
	s_add_i32 s22, 0, 0x1c000
	s_add_i32 s23, s40, s31
	v_add_u32_e32 v184, s22, v245
	ds_read_b128 v[176:179], v184
	ds_read_b128 v[180:183], v184 offset:1024
	ds_read_b128 v[222:225], v184 offset:2048
	ds_read_b128 v[226:229], v184 offset:3072
	s_waitcnt vmcnt(8)
	s_waitcnt lgkmcnt(0)
	s_barrier
	s_setprio 1
	v_mfma_f32_16x16x32_bf16 v[124:127], v[128:131], v[144:147], v[124:127]
	v_mfma_f32_16x16x32_bf16 v[120:123], v[136:139], v[144:147], v[120:123]
	v_mfma_f32_16x16x32_bf16 v[108:111], v[128:131], v[152:155], v[108:111]
	v_mfma_f32_16x16x32_bf16 v[104:107], v[136:139], v[152:155], v[104:107]
	v_mfma_f32_16x16x32_bf16 v[92:95], v[128:131], v[160:163], v[92:95]
	v_mfma_f32_16x16x32_bf16 v[88:91], v[136:139], v[160:163], v[88:91]
	v_mfma_f32_16x16x32_bf16 v[76:79], v[128:131], v[168:171], v[76:79]
	v_mfma_f32_16x16x32_bf16 v[72:75], v[136:139], v[168:171], v[72:75]
	v_mfma_f32_16x16x32_bf16 v[124:127], v[132:135], v[148:151], v[124:127]
	v_mfma_f32_16x16x32_bf16 v[120:123], v[140:143], v[148:151], v[120:123]
	v_mfma_f32_16x16x32_bf16 v[108:111], v[132:135], v[156:159], v[108:111]
	v_mfma_f32_16x16x32_bf16 v[104:107], v[140:143], v[156:159], v[104:107]
	v_mfma_f32_16x16x32_bf16 v[92:95], v[132:135], v[164:167], v[92:95]
	v_mfma_f32_16x16x32_bf16 v[88:91], v[140:143], v[164:167], v[88:91]
	v_mfma_f32_16x16x32_bf16 v[76:79], v[132:135], v[172:175], v[76:79]
	v_mfma_f32_16x16x32_bf16 v[72:75], v[140:143], v[172:175], v[72:75]
	v_mfma_f32_16x16x32_bf16 v[116:119], v[176:179], v[144:147], v[116:119]
	v_mfma_f32_16x16x32_bf16 v[112:115], v[222:225], v[144:147], v[112:115]
	v_mfma_f32_16x16x32_bf16 v[100:103], v[176:179], v[152:155], v[100:103]
	v_mfma_f32_16x16x32_bf16 v[96:99], v[222:225], v[152:155], v[96:99]
	v_mfma_f32_16x16x32_bf16 v[84:87], v[176:179], v[160:163], v[84:87]
	v_mfma_f32_16x16x32_bf16 v[80:83], v[222:225], v[160:163], v[80:83]
	v_mfma_f32_16x16x32_bf16 v[68:71], v[176:179], v[168:171], v[68:71]
	v_mfma_f32_16x16x32_bf16 v[64:67], v[222:225], v[168:171], v[64:67]
	v_mfma_f32_16x16x32_bf16 v[116:119], v[180:183], v[148:151], v[116:119]
	v_mfma_f32_16x16x32_bf16 v[112:115], v[226:229], v[148:151], v[112:115]
	v_mfma_f32_16x16x32_bf16 v[100:103], v[180:183], v[156:159], v[100:103]
	v_mfma_f32_16x16x32_bf16 v[96:99], v[226:229], v[156:159], v[96:99]
	v_mfma_f32_16x16x32_bf16 v[84:87], v[180:183], v[164:167], v[84:87]
	v_mfma_f32_16x16x32_bf16 v[80:83], v[226:229], v[164:167], v[80:83]
	v_mfma_f32_16x16x32_bf16 v[68:71], v[180:183], v[172:175], v[68:71]
	v_mfma_f32_16x16x32_bf16 v[64:67], v[226:229], v[172:175], v[64:67]
	s_setprio 0
	s_barrier
; #define PG8_STAGE(bufoff, gbase, voff) do { _Pragma("unroll") for (int _i = 0; _i < 2; ++_i) \
;         __builtin_amdgcn_global_load_lds((const unsigned*)((const char*)(gbase) + (voff)[_i]), (LAS unsigned*)(lds + (bufoff) + ldsw + _i * 8192), 16, 0, 0); } while (0)
; #define PG8_LDA(dst, b, h) do { _Pragma("unroll") for (int m = 0; m < 4; ++m) _Pragma("unroll") for (int k = 0; k < 2; ++k) dst[m][k] = *(const LAS bf16x8*)(lds + PG8_SA(b, h) + aoff + m * 2048 + k * 1024); } while (0)
; #define PG8_LDB(dst, b, h) do { _Pragma("unroll") for (int n = 0; n < 2; ++n) _Pragma("unroll") for (int k = 0; k < 2; ++k) dst[n][k] = *(const LAS bf16x8*)(lds + PG8_SB(b, h) + boff + n * 2048 + k * 1024); } while (0)
; #define PG8_MMA(ai, bj, At, Bt) do { __builtin_amdgcn_s_setprio(1); _Pragma("unroll") for (int m = 0; m < 4; ++m) _Pragma("unroll") for (int n = 0; n < 2; ++n) _Pragma("unroll") for (int k = 0; k < 2; ++k) \
;         acc[ai][bj][m][n] = __builtin_amdgcn_mfma_f32_16x16x32_bf16(Bt[n][k], At[m][k], acc[ai][bj][m][n], 0, 0, 0); __builtin_amdgcn_s_setprio(0); } while (0)
; #define PG8_WAIT_V(n) asm volatile("s_waitcnt vmcnt(" #n ")" ::: "memory")
; #define PG8_WAIT_L(n) asm volatile("s_waitcnt lgkmcnt(" #n ")" ::: "memory")
; #define PG8_BAR __builtin_amdgcn_s_barrier()
; #define PG8_SCHED __builtin_amdgcn_sched_barrier(0)
; template <class Epi>
; __device__ __forceinline__ void gemm_phase(LAS unsigned char* lds, const Gemm g, const StaticOrder& S, const Epi& E, const bool perm) {
;     ...
;             PG8_LDB(B1, 1, 1); PG8_STAGE(PG8_SB(1, 0), b3, voffB);
;             PG8_BAR; PG8_WAIT_L(0); PG8_MMA(0, 1, At, B1); PG8_BAR;
;             PG8_LDA(At, 1, 1); PG8_STAGE(PG8_SA(1, 0), a3, voffA);
;             PG8_BAR; PG8_WAIT_L(0); PG8_MMA(1, 0, At, B0); PG8_BAR; PG8_SCHED;
;             PG8_STAGE(PG8_SB(1, 1), b3 + hstep, voffB);
;             PG8_WAIT_V(6); PG8_BAR; PG8_MMA(1, 1, At, B1); PG8_BAR;
	ds_read_b128 v[144:147], v248 offset:49152
	ds_read_b128 v[148:151], v248 offset:50176
	ds_read_b128 v[152:155], v248 offset:51200
	ds_read_b128 v[156:159], v248 offset:52224
	ds_read_b128 v[160:163], v248 offset:53248
	ds_read_b128 v[164:167], v248 offset:54272
	ds_read_b128 v[168:171], v248 offset:55296
	ds_read_b128 v[172:175], v248 offset:56320
	v_lshl_add_u64 v[230:231], v[230:231], 0, s[74:75]
	s_mov_b32 m0, s23
	s_nop 0
	global_load_lds_dwordx4 v[230:231], off
	v_lshl_add_u64 v[230:231], v[232:233], 0, s[74:75]
	s_add_i32 m0, s23, 0x2000
	s_nop 0
	global_load_lds_dwordx4 v[230:231], off
	v_lshl_add_u64 v[230:231], v[250:251], 0, s[74:75]
	s_mov_b32 m0, s14
	s_nop 0
	global_load_lds_dwordx4 v[230:231], off
	v_lshl_add_u64 v[230:231], v[252:253], 0, s[74:75]
	s_mov_b32 m0, s15
	s_nop 0
	global_load_lds_dwordx4 v[230:231], off
	s_add_i32 s22, s22, s31
	v_lshl_add_u64 v[230:231], v[238:239], 0, s[74:75]
	s_mov_b32 m0, s22
	s_nop 0
	global_load_lds_dwordx4 v[230:231], off
	v_lshl_add_u64 v[230:231], v[240:241], 0, s[74:75]
	s_add_i32 m0, s22, 0x2000
	s_nop 0
	global_load_lds_dwordx4 v[230:231], off
	s_waitcnt vmcnt(8)
	s_waitcnt lgkmcnt(0)
	s_barrier
	s_setprio 1
	v_mfma_f32_16x16x32_bf16 v[60:63], v[128:131], v[144:147], v[60:63]
	v_mfma_f32_16x16x32_bf16 v[56:59], v[136:139], v[144:147], v[56:59]
	v_mfma_f32_16x16x32_bf16 v[44:47], v[128:131], v[152:155], v[44:47]
	v_mfma_f32_16x16x32_bf16 v[40:43], v[136:139], v[152:155], v[40:43]
	v_mfma_f32_16x16x32_bf16 v[28:31], v[128:131], v[160:163], v[28:31]
	v_mfma_f32_16x16x32_bf16 v[24:27], v[136:139], v[160:163], v[24:27]
	v_mfma_f32_16x16x32_bf16 v[12:15], v[128:131], v[168:171], v[12:15]
	v_mfma_f32_16x16x32_bf16 v[8:11], v[136:139], v[168:171], v[8:11]
	v_mfma_f32_16x16x32_bf16 v[60:63], v[132:135], v[148:151], v[60:63]
	v_mfma_f32_16x16x32_bf16 v[56:59], v[140:143], v[148:151], v[56:59]
	v_mfma_f32_16x16x32_bf16 v[44:47], v[132:135], v[156:159], v[44:47]
	v_mfma_f32_16x16x32_bf16 v[40:43], v[140:143], v[156:159], v[40:43]
	v_mfma_f32_16x16x32_bf16 v[28:31], v[132:135], v[164:167], v[28:31]
	v_mfma_f32_16x16x32_bf16 v[24:27], v[140:143], v[164:167], v[24:27]
	v_mfma_f32_16x16x32_bf16 v[12:15], v[132:135], v[172:175], v[12:15]
	v_mfma_f32_16x16x32_bf16 v[8:11], v[140:143], v[172:175], v[8:11]
	v_mfma_f32_16x16x32_bf16 v[52:55], v[176:179], v[144:147], v[52:55]
	v_mfma_f32_16x16x32_bf16 v[48:51], v[222:225], v[144:147], v[48:51]
	v_mfma_f32_16x16x32_bf16 v[36:39], v[176:179], v[152:155], v[36:39]
	v_mfma_f32_16x16x32_bf16 v[32:35], v[222:225], v[152:155], v[32:35]
	v_mfma_f32_16x16x32_bf16 v[20:23], v[176:179], v[160:163], v[20:23]
	v_mfma_f32_16x16x32_bf16 v[16:19], v[222:225], v[160:163], v[16:19]
	v_mfma_f32_16x16x32_bf16 v[4:7], v[176:179], v[168:171], v[4:7]
	v_mfma_f32_16x16x32_bf16 v[0:3], v[222:225], v[168:171], v[0:3]
	v_mfma_f32_16x16x32_bf16 v[52:55], v[180:183], v[148:151], v[52:55]
	v_mfma_f32_16x16x32_bf16 v[48:51], v[226:229], v[148:151], v[48:51]
	v_mfma_f32_16x16x32_bf16 v[36:39], v[180:183], v[156:159], v[36:39]
	v_mfma_f32_16x16x32_bf16 v[32:35], v[226:229], v[156:159], v[32:35]
	v_mfma_f32_16x16x32_bf16 v[20:23], v[180:183], v[164:167], v[20:23]
	v_mfma_f32_16x16x32_bf16 v[16:19], v[226:229], v[164:167], v[16:19]
	v_mfma_f32_16x16x32_bf16 v[4:7], v[180:183], v[172:175], v[4:7]
	v_mfma_f32_16x16x32_bf16 v[0:3], v[226:229], v[172:175], v[0:3]
	s_setprio 0
	s_addk_i32 s79, 0x80
	s_add_u32 s6, s6, 0x100
	s_addc_u32 s7, s7, 0
	s_add_u32 s55, s55, 0x100
	s_addc_u32 s78, s78, 0
	s_cmp_ge_u32 s61, s65
	s_mov_b32 s60, s61
	s_barrier
	s_cbranch_scc1 .LBB0_470
	s_branch .LBB0_463
